# k20 + lever 4: one static s_setprio 1 for waves 4-7 over the attention phase (reset at phase exit)
# baseline (speedup 1.0000x reference)
.Lattn_entry:
	v_readlane_b32 s0, v253, 16
	s_nop 3
	s_cmp_ge_u32 s0, 4
	s_cbranch_scc0 .Lattn_prio_done
	s_setprio 1

.LBB0_1644:
	s_setprio 0
	s_waitcnt vmcnt(0)
	s_waitcnt vmcnt(63) expcnt(7) lgkmcnt(15)
	s_barrier
	s_mov_b64 s[0:1], exec
	v_readlane_b32 s70, v253, 47
	v_readlane_b32 s76, v253, 43
	v_readlane_b32 s88, v254, 19
	v_readlane_b32 s71, v253, 48
	v_readlane_b32 s79, v253, 46
	v_readlane_b32 s74, v253, 50
	v_readlane_b32 s89, v254, 20
	v_readlane_b32 s90, v254, 21
	v_readlane_b32 s58, v253, 53
	v_readlane_b32 s64, v253, 55
	s_and_b64 s[2:3], s[0:1], s[70:71]
	v_readlane_b32 s77, v253, 44
	v_readlane_b32 s78, v253, 45
	v_readlane_b32 s68, v253, 49
	v_readlane_b32 s75, v253, 51
	v_readlane_b32 s91, v254, 22
	v_readlane_b32 s57, v253, 52
	v_readlane_b32 s59, v253, 54
	v_readlane_b32 s65, v253, 56
	v_readlane_b32 s62, v253, 57
	v_readlane_b32 s66, v253, 58
	v_readlane_b32 s67, v253, 59
	v_readlane_b32 s79, v253, 60
	v_readlane_b32 s82, v253, 61
	v_readlane_b32 s86, v254, 0
	v_readlane_b32 s87, v253, 62
	v_readlane_b32 s89, v253, 63
	s_mov_b64 exec, s[2:3]
	s_cbranch_execz .LBB0_1696
	v_readlane_b32 s4, v253, 40
	s_mov_b32 s18, s68
	s_mov_b64 s[2:3], 0
	v_mov_b32_e32 v0, s4
	s_waitcnt vmcnt(0) expcnt(0) lgkmcnt(0)
	ds_read_b32 v3, v0
	v_readlane_b32 s4, v253, 41
	s_lshl_b64 s[2:3], s[2:3], 2
	s_add_u32 s2, s74, s2
	v_mov_b32_e32 v0, s4
	ds_read_b32 v2, v0
	s_waitcnt lgkmcnt(1)
	v_cmp_ne_u32_e32 vcc, 0, v3
	s_addc_u32 s3, s75, s3
	s_cbranch_vccnz .LBB0_1660
	s_add_u32 s4, s2, 0x1000
	s_addc_u32 s5, s3, 0
	s_add_u32 s6, s2, 0x1100
	s_addc_u32 s7, s3, 0
	s_add_u32 s8, s2, 0x1200
	s_addc_u32 s9, s3, 0
	s_add_u32 s10, s2, 0x1300
	s_addc_u32 s11, s3, 0
	s_mov_b32 s19, 1
	s_branch .LBB0_1648
